# P8: row-tile groups visited in reverse order (ACT rows written last by P7 are read first)
# baseline (speedup 1.0000x reference)
; #define PG8_STAGE(bufoff, gbase, voff) do { _Pragma("unroll") for (int _i = 0; _i < 2; ++_i) \
;         __builtin_amdgcn_global_load_lds((const unsigned*)((const char*)(gbase) + (voff)[_i]), (PG8_LAS unsigned*)(lds + (bufoff) + ldsw + _i * 8192), 16, 0, 0); } while (0)
; #define PG8_WAIT_V(n) asm volatile("s_waitcnt vmcnt(" #n ")" ::: "memory")
; #define PG8_BAR __builtin_amdgcn_s_barrier()
;     __host__ __device__ bool next(int i, Unit& u) const {
;         const long L = (long)i * G + c; if (L >= nwg) return false;
;         int wgid = (int)L; { const int q = nwg / NXCD, r = nwg % NXCD, xcd = wgid % NXCD, off = wgid / NXCD; wgid = (xcd < r ? xcd * (q + 1) : r * (q + 1) + (xcd - r) * q) + off; }
;         const int nig = WGM * nN, gid = wgid / nig, fm = gid * WGM, gsz = (nM - fm) < WGM ? (nM - fm) : WGM;
;         u.pm = fm + ((wgid % nig) % gsz); u.pn = (wgid % nig) / gsz; return true;
; template <class Epi, class Sched, bool ALIGN_EPI = false, bool SP2 = false>
; __device__ __forceinline__ void gemm_phase(PG8_LAS unsigned char* lds, const Gemm g, const Sched& S, const Epi& E) {
;     ...
;     const char* cA = (const char*)g.A + (size_t)cur.pm * tstepA + (size_t)cur.pn * apn; const char* cB = (const char*)g.Bt + (size_t)cur.pn * tstepB;
;     S.a_ready(cur);
;     if constexpr (SP2) {
;         PG8_STAGE(PG8_SB(0, 0), cB, voffB); PG8_STAGE(PG8_SB(0, 1), cB + hstepB, voffB); PG8_STAGE(PG8_SA(0, 0), cA, voffA); PG8_STAGE(PG8_SA(0, 1), cA + hstepA, voffA);
;         if (wr == 1) PG8_BAR;
;         PG8_WAIT_V(2); PG8_BAR;
;         PG8_STAGE(PG8_SB(1, 0), cB + kstep, voffB); PG8_STAGE(PG8_SA(1, 0), cA + kstep, voffA); PG8_STAGE(PG8_SB(1, 1), cB + hstepB + kstep, voffB);
;         PG8_WAIT_V(6); PG8_BAR;
;     } else {
;         PG8_STAGE(PG8_SB(0, 0), cB, voffB); PG8_STAGE(PG8_SA(0, 0), cA, voffA); PG8_STAGE(PG8_SB(0, 1), cB + hstepB, voffB); PG8_STAGE(PG8_SA(0, 1), cA + hstepA, voffA);
;         if (wr == 1) PG8_BAR;
;         PG8_WAIT_V(4); PG8_BAR;
.LBB0_669:
	v_ashrrev_i32_e32 v1, 31, v8
	v_lshrrev_b32_e32 v1, 26, v1
	v_add_u32_e32 v1, v8, v1
	v_ashrrev_i32_e32 v9, 6, v1
	v_bfe_i32 v1, v8, 27, 1
	v_lshlrev_b32_e32 v0, 4, v8
	v_lshrrev_b32_e32 v1, 22, v1
	v_add_u32_e32 v1, v0, v1
	v_and_b32_e32 v1, 0xfffffc00, v1
	v_sub_u32_e32 v1, v0, v1
	v_lshrrev_b32_e32 v2, 4, v1
	v_bitop3_b32 v1, v2, v1, 32 bitop3:0x6c
	v_ashrrev_i32_e32 v3, 31, v1
	v_lshrrev_b32_e32 v3, 26, v3
	v_lshlrev_b32_e32 v2, 3, v9
	v_add_u32_e32 v3, v1, v3
	v_and_b32_e32 v2, -16, v2
	v_ashrrev_i32_e32 v11, 6, v3
	v_and_b32_e32 v3, 0xc0, v3
	v_add_u32_e32 v2, v11, v2
	v_lshlrev_b32_e32 v4, 5, v9
	v_sub_u32_e32 v1, v1, v3
	v_mov_b32_e32 v3, 1
	v_and_b32_e32 v10, 32, v4
	v_ashrrev_i16_sdwa v1, v3, sext(v1) dst_sel:DWORD dst_unused:UNUSED_PAD src0_sel:DWORD src1_sel:BYTE_0
	v_lshlrev_b32_e32 v4, 1, v2
	v_lshrrev_b32_e32 v5, 2, v2
	v_and_b32_e32 v6, 3, v11
	s_mov_b32 s1, 0xffffe0
	v_bfe_i32 v12, v1, 0, 16
	v_and_b32_e32 v4, 24, v4
	v_and_b32_e32 v5, 4, v5
	v_and_or_b32 v6, v2, s1, v6
	s_movk_i32 s3, 0xb00
	v_add_u32_e32 v1, v10, v12
	v_or3_b32 v4, v6, v5, v4
	v_mul_lo_u32 v2, v2, s3
	v_add_lshl_u32 v144, v1, v2, 1
	v_mul_u32_u24_e32 v2, 0xb00, v4
	v_add_u32_e32 v0, 0x2000, v0
	v_add_lshl_u32 v146, v2, v1, 1
	v_ashrrev_i32_e32 v1, 31, v0
	v_lshrrev_b32_e32 v1, 22, v1
	v_add_u32_e32 v1, v0, v1
	v_ashrrev_i32_e32 v13, 10, v1
	v_mul_i32_i24_e32 v1, 0x400, v13
	v_sub_u32_e32 v0, v0, v1
	v_lshrrev_b32_e32 v1, 4, v0
	v_bitop3_b32 v0, v1, v0, 32 bitop3:0x6c
	v_ashrrev_i32_e32 v2, 31, v0
	v_lshrrev_b32_e32 v2, 26, v2
	v_lshlrev_b32_e32 v1, 3, v13
	v_add_u32_e32 v2, v0, v2
	v_and_b32_e32 v1, -16, v1
	v_ashrrev_i32_e32 v14, 6, v2
	v_lshlrev_b32_e32 v4, 5, v13
	v_add_u32_e32 v1, v14, v1
	v_and_b32_e32 v15, 32, v4
	v_and_b32_e32 v4, 3, v14
	s_add_i32 s0, s6, s0
	v_and_or_b32 v4, v1, s1, v4
	s_ashr_i32 s1, s0, 31
	s_lshr_b32 s1, s1, 27
	s_add_i32 s1, s0, s1
	s_ashr_i32 s6, s1, 5
	s_and_b32 s1, s1, 0xffe0
	s_sub_i32 s0, s0, s1
	s_bfe_i32 s1, s0, 0x80000
	s_bfe_u32 s1, s1, 0x3000c
	s_add_i32 s1, s0, s1
	s_bfe_i32 s7, s1, 0x80000
	s_and_b32 s1, s1, 0xf8
	s_sub_i32 s0, s0, s1
	s_lshl_b32 s6, s6, 3
	s_sext_i32_i16 s7, s7
	s_sext_i32_i8 s0, s0
	s_ashr_i32 s4, s2, 6
	v_and_b32_e32 v2, 0xc0, v2
	s_add_i32 s58, s6, s0
	s_xor_b32 s58, s58, 0x18
	s_ashr_i32 s0, s7, 3
	v_sub_u32_e32 v0, v0, v2
	s_ashr_i32 s5, s2, 8
	s_lshl_b32 s23, s4, 10
	s_lshr_b32 s8, s7, 3
	s_mul_hi_i32 s1, s0, 0x160000
	s_mul_i32 s0, s0, 0x160000
	v_ashrrev_i16_sdwa v0, v3, sext(v0) dst_sel:DWORD dst_unused:UNUSED_PAD src0_sel:DWORD src1_sel:BYTE_0
	v_lshlrev_b32_e32 v2, 1, v1
	v_lshrrev_b32_e32 v3, 2, v1
	s_add_u32 s38, s64, s0
	v_bfe_i32 v16, v0, 0, 16
	v_and_b32_e32 v2, 24, v2
	v_and_b32_e32 v3, 4, v3
	s_addc_u32 s39, s65, s1
	s_add_i32 s28, s23, 0
	v_add_u32_e32 v0, v15, v16
	v_or3_b32 v2, v4, v3, v2
	v_mul_lo_u32 v1, v1, s3
	s_add_i32 m0, s28, 0x10000
	v_add_lshl_u32 v148, v0, v1, 1
	v_mul_u32_u24_e32 v1, 0xb00, v2
	global_load_lds_dwordx4 v146, s[38:39]
	s_add_i32 m0, s28, 0x12000
	v_add_lshl_u32 v150, v1, v0, 1
	s_add_u32 s0, s38, 0xb0000
	global_load_lds_dwordx4 v150, s[38:39]
	s_addc_u32 s1, s39, 0
	s_add_i32 m0, s28, 0x14000
	s_mul_i32 s9, s58, 0x160000
	global_load_lds_dwordx4 v146, s[0:1]
	s_add_i32 m0, s28, 0x16000
	s_mul_hi_i32 s6, s58, 0x160000
	s_add_u32 s36, s18, s9
	s_addc_u32 s37, s19, s6
	s_add_i32 s29, s28, 0x2000
	global_load_lds_dwordx4 v150, s[0:1]
	s_mov_b32 m0, s28
	s_add_u32 s0, s36, 0xb0000
	global_load_lds_dwordx4 v144, s[36:37]
	s_mov_b32 m0, s29
	s_addc_u32 s1, s37, 0
	s_add_i32 s30, s28, 0x4000
	global_load_lds_dwordx4 v148, s[36:37]
	s_mov_b32 m0, s30
	s_add_i32 s31, s28, 0x6000
	global_load_lds_dwordx4 v144, s[0:1]
	s_mov_b32 m0, s31
	v_mov_b32_e32 v147, 0
	global_load_lds_dwordx4 v148, s[0:1]
	v_mov_b32_e32 v151, v147
	v_mov_b32_e32 v145, v147
	v_mov_b32_e32 v149, v147
	s_cmp_eq_u32 s5, 1
	s_mov_b32 s35, 0
	v_lshl_add_u64 v[6:7], s[38:39], 0, v[146:147]
	v_lshl_add_u64 v[4:5], s[38:39], 0, v[150:151]
	v_lshl_add_u64 v[0:1], s[36:37], 0, v[144:145]
	s_cselect_b64 s[0:1], -1, 0
	s_cmp_lg_u32 s5, 1
	v_lshl_add_u64 v[2:3], s[36:37], 0, v[148:149]
	s_cbranch_scc1 .LBB0_671
	s_barrier

;     __host__ __device__ bool next(int i, Unit& u) const {
;         const long L = (long)i * G + c; if (L >= nwg) return false;
;         int wgid = (int)L; { const int q = nwg / NXCD, r = nwg % NXCD, xcd = wgid % NXCD, off = wgid / NXCD; wgid = (xcd < r ? xcd * (q + 1) : r * (q + 1) + (xcd - r) * q) + off; }
;         const int nig = WGM * nN, gid = wgid / nig, fm = gid * WGM, gsz = (nM - fm) < WGM ? (nM - fm) : WGM;
;         u.pm = fm + ((wgid % nig) % gsz); u.pn = (wgid % nig) / gsz; return true;
; template <class Epi, class Sched, bool ALIGN_EPI = false, bool SP2 = false>
; __device__ __forceinline__ void gemm_phase(PG8_LAS unsigned char* lds, const Gemm g, const Sched& S, const Epi& E) {
;     ...
;         const bool has_next = S.next(ui + 1, nxt);
;         const char* nA = has_next ? (const char*)g.A + (size_t)nxt.pm * tstepA + (size_t)nxt.pn * apn : cA; const char* nB = has_next ? (const char*)g.Bt + (size_t)nxt.pn * tstepB : cB;
.LBB0_679:
	s_ashr_i32 s2, s24, 3
	s_add_i32 s2, s40, s2
	s_ashr_i32 s3, s2, 31
	s_lshr_b32 s3, s3, 27
	s_add_i32 s3, s2, s3
	s_ashr_i32 s24, s3, 5
	s_lshl_b32 s24, s24, 3
	s_sub_i32 s25, 0x100, s24
	s_min_i32 s25, s25, 8
	s_abs_i32 s33, s25
	v_cvt_f32_u32_e32 v0, s33
	s_sub_i32 s41, 0, s33
	s_andn2_b32 s3, s3, 31
	s_sub_i32 s2, s2, s3
	v_rcp_iflag_f32_e32 v0, v0
	s_abs_i32 s3, s2
	s_xor_b32 s40, s2, s25
	s_ashr_i32 s40, s40, 31
	v_mul_f32_e32 v0, 0x4f7ffffe, v0
	v_cvt_u32_f32_e32 v0, v0
	s_nop 0
	v_readfirstlane_b32 s42, v0
	s_mul_i32 s41, s41, s42
	s_mul_hi_u32 s41, s42, s41
	s_add_i32 s42, s42, s41
	s_mul_hi_u32 s41, s3, s42
	s_mul_i32 s42, s41, s33
	s_sub_i32 s3, s3, s42
	s_add_i32 s43, s41, 1
	s_sub_i32 s42, s3, s33
	s_cmp_ge_u32 s3, s33
	s_cselect_b32 s41, s43, s41
	s_cselect_b32 s3, s42, s3
	s_add_i32 s42, s41, 1
	s_cmp_ge_u32 s3, s33
	s_cselect_b32 s3, s42, s41
	s_xor_b32 s3, s3, s40
	s_sub_i32 s56, s3, s40
	s_mul_i32 s3, s56, s25
	s_sub_i32 s2, s2, s3
	s_add_i32 s57, s24, s2
	s_xor_b32 s57, s57, 0x18
